# cache-policy hint: nt on the attention output stores
# speedup vs baseline: 1.0060x; 1.0011x over previous
; __device__ __forceinline__ unsigned cvt_pk_bf16(float lo, float hi) { const f32x2_t f = {lo, hi}; const bf16x2_t b = __builtin_convertvector(f, bf16x2_t); return __builtin_bit_cast(unsigned, b); }
; __device__ __forceinline__ void p4_attn(const Params& p, LAS unsigned char* lds, const int dummy) {
;     ...
;         for (int ps = 0; ps < 5; ++ps) {
;             if (2 * ps + 1 >= ilo) {
;                 u32x4 bw; bw.x = cvt_pk_bf16(sT[2 * ps][0], sT[2 * ps][1]); bw.y = cvt_pk_bf16(sT[2 * ps][2], sT[2 * ps][3]);
;                 if (ps < 4) { bw.z = cvt_pk_bf16(sT[(2 * ps + 1) % 9][0], sT[(2 * ps + 1) % 9][1]); bw.w = cvt_pk_bf16(sT[(2 * ps + 1) % 9][2], sT[(2 * ps + 1) % 9][3]); } else { bw.z = 0u; bw.w = 0u; }
;                 const bf16x8 bfrag = __builtin_bit_cast(bf16x8, bw);
;                 u32x2 vlo[8], vhi[8];
; #pragma unroll
;                 for (int et = 0; et < 8; ++et) {
;                     vlo[et] = tr_read(VB + (16 * (wid + 2 * ps) + 4 * q + (r >> 2)) * VB_STRIDE + (16 * et + 4 * (r & 3)) * 2);
;                     vhi[et] = (u32x2){0u, 0u};
;                     if (ps < 4) vhi[et] = tr_read(VB + (16 * (wid + 2 * ps + 1) + 4 * q + (r >> 2)) * VB_STRIDE + (16 * et + 4 * (r & 3)) * 2);
;                 }
;                 __builtin_amdgcn_sched_barrier(0);
; #pragma unroll
;                 for (int et = 0; et < 8; ++et) {
;                     u32x4 aw; aw.x = vlo[et].x; aw.y = vlo[et].y; aw.z = vhi[et].x; aw.w = vhi[et].y;
;                     oacc[et] = __builtin_amdgcn_mfma_f32_16x16x32_bf16(__builtin_bit_cast(bf16x8, aw), bfrag, oacc[et], 0, 0, 0);
;                 }
;                 __builtin_amdgcn_sched_barrier(0);
;             }
;         }
;         const float rl = 1.0f / lsum;
;         {
;             bf16_t* odst = dummy ? (bf16_t*)((unsigned char*)p.out + 8388608 + ((tq * 1536 + qcol) * 2 & 16777215)) : R1 + tq * QZ_LD + qcol;
; #pragma unroll
;             for (int et = 0; et < 8; ++et) {
;                 u32x2 w; w.x = cvt_pk_bf16(oacc[et][0] * rl, oacc[et][1] * rl); w.y = cvt_pk_bf16(oacc[et][2] * rl, oacc[et][3] * rl);
;                 *(u32x2*)(odst + 16 * et + 4 * q) = w;
;             }
;             if (q == 0) { float2 mlv; mlv.x = mx; mlv.y = lsum; *(float2*)(ML + (tq * 12 + g * 4 + hh) * 2) = mlv; }
.LBB0_626:
	s_add_i32 s98, s98, 1
	ds_read_b64_tr_b16 v[104:105], v197
	ds_read_b64_tr_b16 v[108:109], v197 offset:32
	ds_read_b64_tr_b16 v[202:203], v197 offset:64
	ds_read_b64_tr_b16 v[206:207], v197 offset:96
	ds_read_b64_tr_b16 v[214:215], v197 offset:128
	ds_read_b64_tr_b16 v[218:219], v197 offset:160
	ds_read_b64_tr_b16 v[222:223], v197 offset:192
	ds_read_b64_tr_b16 v[226:227], v197 offset:224
	v_cvt_pk_bf16_f32 v100, v100, v101
	v_cvt_pk_bf16_f32 v101, v102, v103
	v_mov_b32_e32 v102, v36
	v_mov_b32_e32 v103, v36
	v_mov_b32_e32 v106, v36
	v_mov_b32_e32 v107, v36
	v_mov_b32_e32 v110, v36
	v_mov_b32_e32 v111, v36
	v_mov_b32_e32 v204, v36
	v_mov_b32_e32 v205, v36
	v_mov_b32_e32 v208, v36
	v_mov_b32_e32 v209, v36
	v_mov_b32_e32 v216, v36
	v_mov_b32_e32 v217, v36
	v_mov_b32_e32 v220, v36
	v_mov_b32_e32 v221, v36
	v_mov_b32_e32 v224, v36
	v_mov_b32_e32 v225, v36
	v_mov_b32_e32 v228, v36
	v_mov_b32_e32 v229, v36
	s_waitcnt lgkmcnt(7)
	v_mfma_f32_16x16x32_bf16 v[96:99], v[104:107], v[100:103], v[96:99]
	s_waitcnt lgkmcnt(6)
	v_mfma_f32_16x16x32_bf16 v[92:95], v[108:111], v[100:103], v[92:95]
	s_waitcnt lgkmcnt(5)
	v_mfma_f32_16x16x32_bf16 v[88:91], v[202:205], v[100:103], v[88:91]
	s_waitcnt lgkmcnt(4)
	v_mfma_f32_16x16x32_bf16 v[84:87], v[206:209], v[100:103], v[84:87]
	s_waitcnt lgkmcnt(3)
	v_mfma_f32_16x16x32_bf16 v[80:83], v[214:217], v[100:103], v[80:83]
	s_waitcnt lgkmcnt(2)
	v_mfma_f32_16x16x32_bf16 v[76:79], v[218:221], v[100:103], v[76:79]
	s_waitcnt lgkmcnt(1)
	v_mfma_f32_16x16x32_bf16 v[72:75], v[222:225], v[100:103], v[72:75]
	s_waitcnt lgkmcnt(0)
	v_mfma_f32_16x16x32_bf16 v[68:71], v[226:229], v[100:103], v[68:71]
	v_add_f32_e32 v39, v37, v39
	v_div_scale_f32 v37, s[0:1], v39, v39, 1.0
	v_rcp_f32_e32 v100, v37
	v_div_scale_f32 v101, vcc, 1.0, v39, 1.0
	v_mov_b32_e32 v123, v36
	v_fma_f32 v102, -v37, v100, 1.0
	v_fmac_f32_e32 v100, v102, v100
	v_mul_f32_e32 v102, v101, v100
	v_fma_f32 v103, -v37, v102, v101
	v_fmac_f32_e32 v102, v103, v100
	v_fma_f32 v37, -v37, v102, v101
	v_div_fmas_f32 v37, v37, v100, v102
	v_div_fixup_f32 v100, v37, v39, 1.0
	v_pk_mul_f32 v[96:97], v[100:101], v[96:97] op_sel_hi:[0,1]
	v_pk_mul_f32 v[98:99], v[100:101], v[98:99] op_sel_hi:[0,1]
	v_pk_mul_f32 v[92:93], v[100:101], v[92:93] op_sel_hi:[0,1]
	v_pk_mul_f32 v[94:95], v[100:101], v[94:95] op_sel_hi:[0,1]
	v_pk_mul_f32 v[88:89], v[100:101], v[88:89] op_sel_hi:[0,1]
	v_pk_mul_f32 v[90:91], v[100:101], v[90:91] op_sel_hi:[0,1]
	v_pk_mul_f32 v[84:85], v[100:101], v[84:85] op_sel_hi:[0,1]
	v_pk_mul_f32 v[86:87], v[100:101], v[86:87] op_sel_hi:[0,1]
	v_pk_mul_f32 v[80:81], v[100:101], v[80:81] op_sel_hi:[0,1]
	v_pk_mul_f32 v[82:83], v[100:101], v[82:83] op_sel_hi:[0,1]
	v_pk_mul_f32 v[76:77], v[100:101], v[76:77] op_sel_hi:[0,1]
	v_pk_mul_f32 v[78:79], v[100:101], v[78:79] op_sel_hi:[0,1]
	v_pk_mul_f32 v[72:73], v[100:101], v[72:73] op_sel_hi:[0,1]
	v_pk_mul_f32 v[74:75], v[100:101], v[74:75] op_sel_hi:[0,1]
	v_pk_mul_f32 v[68:69], v[100:101], v[68:69] op_sel_hi:[0,1]
	v_pk_mul_f32 v[70:71], v[100:101], v[70:71] op_sel_hi:[0,1]
	v_lshl_add_u64 v[102:103], v[126:127], 0, v[122:123]
	v_cvt_pk_bf16_f32 v96, v96, v97
	v_cvt_pk_bf16_f32 v97, v98, v99
	v_cvt_pk_bf16_f32 v98, v92, v93
	v_cvt_pk_bf16_f32 v99, v94, v95
	v_cvt_pk_bf16_f32 v88, v88, v89
	v_cvt_pk_bf16_f32 v89, v90, v91
	v_cvt_pk_bf16_f32 v90, v84, v85
	v_cvt_pk_bf16_f32 v91, v86, v87
	v_cvt_pk_bf16_f32 v80, v80, v81
	v_cvt_pk_bf16_f32 v81, v82, v83
	v_cvt_pk_bf16_f32 v82, v76, v77
	v_cvt_pk_bf16_f32 v83, v78, v79
	v_cvt_pk_bf16_f32 v72, v72, v73
	v_cvt_pk_bf16_f32 v73, v74, v75
	v_cvt_pk_bf16_f32 v74, v68, v69
	v_cvt_pk_bf16_f32 v75, v70, v71
	v_mbcnt_lo_u32_b32 v92, -1, 0
	v_mbcnt_hi_u32_b32 v92, -1, v92
	v_and_b32_e32 v92, 16, v92
	v_lshrrev_b32_e32 v93, 1, v92
	v_add_u32_e32 v92, v92, v93
	v_mov_b32_e32 v93, 0
	v_permlane16_swap_b32 v96, v98
	v_permlane16_swap_b32 v97, v99
	v_permlane16_swap_b32 v88, v90
	v_permlane16_swap_b32 v89, v91
	v_permlane16_swap_b32 v80, v82
	v_permlane16_swap_b32 v81, v83
	v_permlane16_swap_b32 v72, v74
	v_permlane16_swap_b32 v73, v75
	v_lshl_add_u64 v[102:103], v[102:103], 0, v[92:93]
	s_nop 1
	global_store_dwordx4 v[102:103], v[96:99], off nt
	global_store_dwordx4 v[102:103], v[88:91], off offset:64 nt
	global_store_dwordx4 v[102:103], v[80:83], off offset:128 nt
	global_store_dwordx4 v[102:103], v[72:75], off offset:192 nt
	s_nop 1
	s_and_saveexec_b64 s[0:1], s[16:17]
	s_cbranch_execz .LBB0_591
	s_lshl_b32 s4, s9, 2
	s_ashr_i32 s5, s4, 31
	v_mov_b32_e32 v68, s4
	v_mov_b32_e32 v69, s5
	v_mad_i64_i32 v[68:69], s[4:5], v124, 12, v[68:69]
	s_mov_b32 s4, s14
	s_mov_b32 s5, s15
	s_mov_b64 s[6:7], s[16:17]
	s_mov_b32 s9, s18
	v_readlane_b32 s12, v254, 29
	v_or_b32_e32 v68, s10, v68
	v_readlane_b32 s14, v254, 31
	v_readlane_b32 s15, v254, 32
	v_readlane_b32 s16, v254, 33
	v_readlane_b32 s17, v254, 34
	v_readlane_b32 s18, v254, 35
	v_readlane_b32 s19, v254, 36
	s_mov_b64 s[16:17], s[6:7]
	s_mov_b32 s15, s5
	s_mov_b32 s14, s4
	v_lshl_add_u64 v[68:69], v[68:69], 3, s[18:19]
	s_mov_b32 s18, s9
	v_readlane_b32 s13, v254, 30
	global_store_dwordx2 v[68:69], v[38:39], off
	s_branch .LBB0_591
